# layer-0 out-projection epilogue: non-temporal hint on the output stores too (next read a whole layer later)
# speedup vs baseline: 1.0001x; 1.0001x over previous
; DI int grow_of(int lrow, int seg) { return (lrow / SEG) * S + seg * SEG + (lrow % SEG); }
;     DI void operator()(const f32x4 (&acc)[2][2][4][2], const Unit& u, int wr, int wc, int fr, int fq) const {
;         const int b = u.pm / TPB;
;         const int lrow0 = u.pm * BM + wr * 64 + fr;
;         const int col0 = u.pn * BM + wc * 32 + 8 * fq;
;         f32x4 gv[2][2];
; #pragma unroll
;         for (int bj = 0; bj < 2; ++bj)
; #pragma unroll
;             for (int n = 0; n < 2; ++n) gv[bj][n] = *(const f32x4*)(gate + b * 3072 + col0 + bj * HALF + 4 * n);
; #pragma unroll
;         for (int ai = 0; ai < 2; ++ai)
; #pragma unroll
;             for (int m = 0; m < 4; ++m) {
;                 const size_t off = (size_t)grow_of(lrow0 + ai * HALF + m * 16, seg) * D + col0;
; #pragma unroll
;                 for (int bj = 0; bj < 2; ++bj)
; #pragma unroll
;                     for (int n = 0; n < 2; ++n) {
;                         const f32x4 xo = *(const f32x4*)(xin + off + bj * HALF + 4 * n);
;                         *(f32x4*)(xout + off + bj * HALF + 4 * n) = xo + gv[bj][n] * acc[ai][bj][m][n];
;                     }
;             }
;     }
.LBB0_794:
	v_lshl_add_u32 v163, s30, 8, v158
	v_ashrrev_i32_e32 v130, 31, v163
	v_lshrrev_b32_e32 v180, 20, v130
	s_ashr_i32 s6, s30, 31
	v_add_u32_e32 v130, v163, v180
	s_lshr_b32 s6, s6, 28
	v_ashrrev_i32_e32 v130, 12, v130
	s_add_i32 s6, s30, s6
	v_lshlrev_b32_e32 v131, 13, v130
	v_mul_i32_i24_e32 v130, 0x1000, v130
	s_lshr_b32 s6, s6, 4
	v_sub_u32_e32 v130, v163, v130
	s_mul_i32 s18, s6, 0xc00
	v_add3_u32 v130, v130, s84, v131
	v_lshl_or_b32 v156, s31, 8, v160
	s_ashr_i32 s19, s18, 31
	v_ashrrev_i32_e32 v131, 31, v130
	s_lshl_b64 s[18:19], s[18:19], 2
	v_ashrrev_i32_e32 v157, 31, v156
	v_lshlrev_b64 v[130:131], 10, v[130:131]
	s_add_u32 s18, s33, s18
	v_readlane_b32 s6, v250, 40
	v_lshl_add_u64 v[130:131], v[130:131], 0, v[156:157]
	s_addc_u32 s19, s6, s19
	v_lshlrev_b64 v[172:173], 2, v[130:131]
	v_lshl_add_u64 v[134:135], v[156:157], 2, s[18:19]
	global_load_dwordx4 v[142:145], v[134:135], off
	global_load_dwordx4 v[138:141], v[134:135], off offset:16
	global_load_dwordx4 v[130:133], v[134:135], off offset:528
	s_nop 0
	global_load_dwordx4 v[134:137], v[134:135], off offset:512
	s_and_b64 vcc, exec, s[42:43]
	s_mov_b64 s[42:43], -1
	s_mov_b32 s39, 0x3fb8aa3b
	v_add_u32_e32 v173, 0x10000, v172
	v_add_u32_e32 v174, 0x20000, v172
	v_add_u32_e32 v175, 0x30000, v172
	v_add_u32_e32 v176, 0x80000, v172
	v_add_u32_e32 v177, 0x90000, v172
	v_add_u32_e32 v178, 0xa0000, v172
	v_add_u32_e32 v179, 0xb0000, v172
	global_load_dwordx4 v[180:183], v172, s[4:5] nt
	global_load_dwordx4 v[184:187], v172, s[4:5] offset:16 nt
	global_load_dwordx4 v[188:191], v172, s[4:5] offset:512 nt
	global_load_dwordx4 v[192:195], v172, s[4:5] offset:528 nt
	global_load_dwordx4 v[218:221], v173, s[4:5] nt
	global_load_dwordx4 v[222:225], v173, s[4:5] offset:16 nt
	global_load_dwordx4 v[226:229], v173, s[4:5] offset:512 nt
	global_load_dwordx4 v[230:233], v173, s[4:5] offset:528 nt
	global_load_dwordx4 v[234:237], v174, s[4:5] nt
	global_load_dwordx4 v[238:241], v174, s[4:5] offset:16 nt
	global_load_dwordx4 v[242:245], v174, s[4:5] offset:512 nt
	global_load_dwordx4 v[246:249], v174, s[4:5] offset:528 nt
	s_waitcnt vmcnt(8)
	v_pk_fma_f32 v[180:181], v[126:127], v[142:143], v[180:181]
	v_pk_fma_f32 v[182:183], v[128:129], v[144:145], v[182:183]
	v_pk_fma_f32 v[184:185], v[122:123], v[138:139], v[184:185]
	v_pk_fma_f32 v[186:187], v[124:125], v[140:141], v[186:187]
	v_pk_fma_f32 v[188:189], v[118:119], v[134:135], v[188:189]
	v_pk_fma_f32 v[190:191], v[120:121], v[136:137], v[190:191]
	v_pk_fma_f32 v[192:193], v[106:107], v[130:131], v[192:193]
	v_pk_fma_f32 v[194:195], v[108:109], v[132:133], v[194:195]
	global_store_dwordx4 v172, v[180:183], s[74:75] nt
	global_store_dwordx4 v172, v[184:187], s[74:75] offset:16 nt
	global_store_dwordx4 v172, v[188:191], s[74:75] offset:512 nt
	global_store_dwordx4 v172, v[192:195], s[74:75] offset:528 nt
	s_nop 1
	global_load_dwordx4 v[180:183], v175, s[4:5] nt
	global_load_dwordx4 v[184:187], v175, s[4:5] offset:16 nt
	global_load_dwordx4 v[188:191], v175, s[4:5] offset:512 nt
	global_load_dwordx4 v[192:195], v175, s[4:5] offset:528 nt
	s_waitcnt vmcnt(12)
	v_pk_fma_f32 v[218:219], v[114:115], v[142:143], v[218:219]
	v_pk_fma_f32 v[220:221], v[116:117], v[144:145], v[220:221]
	v_pk_fma_f32 v[222:223], v[110:111], v[138:139], v[222:223]
	v_pk_fma_f32 v[224:225], v[112:113], v[140:141], v[224:225]
	v_pk_fma_f32 v[226:227], v[102:103], v[134:135], v[226:227]
	v_pk_fma_f32 v[228:229], v[104:105], v[136:137], v[228:229]
	v_pk_fma_f32 v[230:231], v[90:91], v[130:131], v[230:231]
	v_pk_fma_f32 v[232:233], v[92:93], v[132:133], v[232:233]
	global_store_dwordx4 v173, v[218:221], s[74:75] nt
	global_store_dwordx4 v173, v[222:225], s[74:75] offset:16 nt
	global_store_dwordx4 v173, v[226:229], s[74:75] offset:512 nt
	global_store_dwordx4 v173, v[230:233], s[74:75] offset:528 nt
	s_nop 1
	global_load_dwordx4 v[218:221], v176, s[4:5] nt
	global_load_dwordx4 v[222:225], v176, s[4:5] offset:16 nt
	global_load_dwordx4 v[226:229], v176, s[4:5] offset:512 nt
	global_load_dwordx4 v[230:233], v176, s[4:5] offset:528 nt
	s_waitcnt vmcnt(16)
	v_pk_fma_f32 v[234:235], v[98:99], v[142:143], v[234:235]
	v_pk_fma_f32 v[236:237], v[100:101], v[144:145], v[236:237]
	v_pk_fma_f32 v[238:239], v[94:95], v[138:139], v[238:239]
	v_pk_fma_f32 v[240:241], v[96:97], v[140:141], v[240:241]
	v_pk_fma_f32 v[242:243], v[86:87], v[134:135], v[242:243]
	v_pk_fma_f32 v[244:245], v[88:89], v[136:137], v[244:245]
	v_pk_fma_f32 v[246:247], v[74:75], v[130:131], v[246:247]
	v_pk_fma_f32 v[248:249], v[76:77], v[132:133], v[248:249]
	global_store_dwordx4 v174, v[234:237], s[74:75] nt
	global_store_dwordx4 v174, v[238:241], s[74:75] offset:16 nt
	global_store_dwordx4 v174, v[242:245], s[74:75] offset:512 nt
	global_store_dwordx4 v174, v[246:249], s[74:75] offset:528 nt
	s_nop 1
	global_load_dwordx4 v[234:237], v177, s[4:5] nt
	global_load_dwordx4 v[238:241], v177, s[4:5] offset:16 nt
	global_load_dwordx4 v[242:245], v177, s[4:5] offset:512 nt
	global_load_dwordx4 v[246:249], v177, s[4:5] offset:528 nt
	s_waitcnt vmcnt(16)
; DI int grow_of(int lrow, int seg) { return (lrow / SEG) * S + seg * SEG + (lrow % SEG); }
;     DI void operator()(const f32x4 (&acc)[2][2][4][2], const Unit& u, int wr, int wc, int fr, int fq) const {
;         const int b = u.pm / TPB;
;         const int lrow0 = u.pm * BM + wr * 64 + fr;
;         const int col0 = u.pn * BM + wc * 32 + 8 * fq;
;         f32x4 gv[2][2];
; #pragma unroll
;         for (int bj = 0; bj < 2; ++bj)
; #pragma unroll
;             for (int n = 0; n < 2; ++n) gv[bj][n] = *(const f32x4*)(gate + b * 3072 + col0 + bj * HALF + 4 * n);
; #pragma unroll
;         for (int ai = 0; ai < 2; ++ai)
; #pragma unroll
;             for (int m = 0; m < 4; ++m) {
;                 const size_t off = (size_t)grow_of(lrow0 + ai * HALF + m * 16, seg) * D + col0;
; #pragma unroll
;                 for (int bj = 0; bj < 2; ++bj)
; #pragma unroll
;                     for (int n = 0; n < 2; ++n) {
;                         const f32x4 xo = *(const f32x4*)(xin + off + bj * HALF + 4 * n);
;                         *(f32x4*)(xout + off + bj * HALF + 4 * n) = xo + gv[bj][n] * acc[ai][bj][m][n];
;                     }
;             }
;     }
	v_pk_fma_f32 v[180:181], v[82:83], v[142:143], v[180:181]
	v_pk_fma_f32 v[182:183], v[84:85], v[144:145], v[182:183]
	v_pk_fma_f32 v[184:185], v[78:79], v[138:139], v[184:185]
	v_pk_fma_f32 v[186:187], v[80:81], v[140:141], v[186:187]
	v_pk_fma_f32 v[188:189], v[70:71], v[134:135], v[188:189]
	v_pk_fma_f32 v[190:191], v[72:73], v[136:137], v[190:191]
	v_pk_fma_f32 v[192:193], v[66:67], v[130:131], v[192:193]
	v_pk_fma_f32 v[194:195], v[68:69], v[132:133], v[194:195]
	global_store_dwordx4 v175, v[180:183], s[74:75] nt
	global_store_dwordx4 v175, v[184:187], s[74:75] offset:16 nt
	global_store_dwordx4 v175, v[188:191], s[74:75] offset:512 nt
	global_store_dwordx4 v175, v[192:195], s[74:75] offset:528 nt
	s_nop 1
	global_load_dwordx4 v[180:183], v178, s[4:5] nt
	global_load_dwordx4 v[184:187], v178, s[4:5] offset:16 nt
	global_load_dwordx4 v[188:191], v178, s[4:5] offset:512 nt
	global_load_dwordx4 v[192:195], v178, s[4:5] offset:528 nt
	s_waitcnt vmcnt(16)
	v_pk_fma_f32 v[218:219], v[62:63], v[142:143], v[218:219]
	v_pk_fma_f32 v[220:221], v[64:65], v[144:145], v[220:221]
	v_pk_fma_f32 v[222:223], v[58:59], v[138:139], v[222:223]
	v_pk_fma_f32 v[224:225], v[60:61], v[140:141], v[224:225]
	v_pk_fma_f32 v[226:227], v[54:55], v[134:135], v[226:227]
	v_pk_fma_f32 v[228:229], v[56:57], v[136:137], v[228:229]
	v_pk_fma_f32 v[230:231], v[42:43], v[130:131], v[230:231]
	v_pk_fma_f32 v[232:233], v[44:45], v[132:133], v[232:233]
	global_store_dwordx4 v176, v[218:221], s[74:75] nt
	global_store_dwordx4 v176, v[222:225], s[74:75] offset:16 nt
	global_store_dwordx4 v176, v[226:229], s[74:75] offset:512 nt
	global_store_dwordx4 v176, v[230:233], s[74:75] offset:528 nt
	s_nop 1
	global_load_dwordx4 v[218:221], v179, s[4:5] nt
	global_load_dwordx4 v[222:225], v179, s[4:5] offset:16 nt
	global_load_dwordx4 v[226:229], v179, s[4:5] offset:512 nt
	global_load_dwordx4 v[230:233], v179, s[4:5] offset:528 nt
	s_waitcnt vmcnt(16)
	v_pk_fma_f32 v[234:235], v[50:51], v[142:143], v[234:235]
	v_pk_fma_f32 v[236:237], v[52:53], v[144:145], v[236:237]
	v_pk_fma_f32 v[238:239], v[46:47], v[138:139], v[238:239]
	v_pk_fma_f32 v[240:241], v[48:49], v[140:141], v[240:241]
	v_pk_fma_f32 v[242:243], v[38:39], v[134:135], v[242:243]
	v_pk_fma_f32 v[244:245], v[40:41], v[136:137], v[244:245]
	v_pk_fma_f32 v[246:247], v[26:27], v[130:131], v[246:247]
	v_pk_fma_f32 v[248:249], v[28:29], v[132:133], v[248:249]
	global_store_dwordx4 v177, v[234:237], s[74:75] nt
	global_store_dwordx4 v177, v[238:241], s[74:75] offset:16 nt
	global_store_dwordx4 v177, v[242:245], s[74:75] offset:512 nt
	global_store_dwordx4 v177, v[246:249], s[74:75] offset:528 nt
	s_waitcnt vmcnt(12)
	v_pk_fma_f32 v[180:181], v[34:35], v[142:143], v[180:181]
	v_pk_fma_f32 v[182:183], v[36:37], v[144:145], v[182:183]
	v_pk_fma_f32 v[184:185], v[30:31], v[138:139], v[184:185]
	v_pk_fma_f32 v[186:187], v[32:33], v[140:141], v[186:187]
	v_pk_fma_f32 v[188:189], v[22:23], v[134:135], v[188:189]
	v_pk_fma_f32 v[190:191], v[24:25], v[136:137], v[190:191]
	v_pk_fma_f32 v[192:193], v[10:11], v[130:131], v[192:193]
	v_pk_fma_f32 v[194:195], v[12:13], v[132:133], v[194:195]
	global_store_dwordx4 v178, v[180:183], s[74:75] nt
	global_store_dwordx4 v178, v[184:187], s[74:75] offset:16 nt
	global_store_dwordx4 v178, v[188:191], s[74:75] offset:512 nt
	global_store_dwordx4 v178, v[192:195], s[74:75] offset:528 nt
	s_waitcnt vmcnt(8)
	v_pk_fma_f32 v[218:219], v[18:19], v[142:143], v[218:219]
	v_pk_fma_f32 v[220:221], v[20:21], v[144:145], v[220:221]
	v_pk_fma_f32 v[222:223], v[14:15], v[138:139], v[222:223]
	v_pk_fma_f32 v[224:225], v[16:17], v[140:141], v[224:225]
	v_pk_fma_f32 v[226:227], v[6:7], v[134:135], v[226:227]
	v_pk_fma_f32 v[228:229], v[8:9], v[136:137], v[228:229]
	v_pk_fma_f32 v[230:231], v[2:3], v[130:131], v[230:231]
	v_pk_fma_f32 v[232:233], v[4:5], v[132:133], v[232:233]
	global_store_dwordx4 v179, v[218:221], s[74:75] nt
	global_store_dwordx4 v179, v[222:225], s[74:75] offset:16 nt
	global_store_dwordx4 v179, v[226:229], s[74:75] offset:512 nt
	global_store_dwordx4 v179, v[230:233], s[74:75] offset:528 nt
	s_cbranch_vccnz .LBB0_781
	s_andn2_b64 vcc, exec, s[0:1]
	s_cbranch_vccnz .LBB0_780
	s_barrier
	s_branch .LBB0_780
